# hgrn combine behind the mixer phase for layer 1 only (layer 0 unchanged: its idle slots already hold the weight conversion)
# baseline (speedup 1.0000x reference)
.LBB0_111:
.LBB0_112:
	s_add_i32 s36, s6, 1
	s_cmp_eq_u32 s6, 34
	s_cbranch_scc1 .LBB0_11
	s_cmp_ge_i32 s36, s7
	s_cbranch_scc1 .LBB0_11
	v_readlane_b32 s4, v253, 46
	v_readlane_b32 s5, v253, 47
	s_andn2_b64 vcc, exec, s[4:5]
	s_cbranch_vccnz .LBB0_125
	s_waitcnt lgkmcnt(0)
	s_barrier
	s_mov_b64 s[4:5], exec
	v_readlane_b32 s20, v253, 48
	v_readlane_b32 s21, v253, 49
	s_and_b64 s[20:21], s[4:5], s[20:21]
	s_mov_b64 exec, s[20:21]
	s_cbranch_execz .LBB0_124
	v_readlane_b32 s12, v252, 0
	v_readlane_b32 s13, v252, 1
	buffer_wbl2 sc1
	s_waitcnt vmcnt(0)
	s_load_dwordx2 s[20:21], s[12:13], 0x58
	s_mov_b64 s[22:23], exec
	v_mbcnt_lo_u32_b32 v2, s22, 0
	v_mbcnt_hi_u32_b32 v2, s23, v2
	v_cmp_eq_u32_e32 vcc, 0, v2
	s_waitcnt lgkmcnt(0)
	global_load_dword v0, v1, s[20:21] offset:40
	s_and_saveexec_b64 s[24:25], vcc
	s_cbranch_execz .LBB0_117
	s_bcnt1_i32_b64 s6, s[22:23]
	v_mov_b32_e32 v3, s6
	global_atomic_add v3, v1, v3, s[20:21] offset:32 sc0

.LBB0_217:
	s_andn2_b64 vcc, exec, s[4:5]
	s_cbranch_vccnz .LBB0_534
	v_readlane_b32 s4, v255, 1
	s_cmp_lt_i32 s4, 2
	s_mov_b64 s[4:5], -1
	s_cbranch_scc1 .LBB0_507
	v_readlane_b32 s4, v255, 1
	s_cmp_lt_i32 s4, 3
	s_mov_b64 s[4:5], -1
	s_cbranch_scc1 .LBB0_309
	v_readlane_b32 s4, v255, 1
	s_cmp_gt_i32 s4, 3
	s_mov_b64 s[4:5], -1
	s_cbranch_scc0 .LBB0_225
	v_readlane_b32 s28, v252, 22
	v_readlane_b32 s44, v252, 4
	s_cmp_eq_u32 s6, 35
	s_cselect_b32 s98, 0x100, 0
	s_cmp_lt_i32 s71, s98
	v_readlane_b32 s29, v252, 23
	v_readlane_b32 s30, v254, 39
	s_movk_i32 s31, 0x1400
	s_mov_b64 s[34:35], 0x6c26000
	s_mov_b32 s2, 0x6c26000
	v_readlane_b32 s45, v252, 5
	v_readlane_b32 s46, v252, 6
	v_readlane_b32 s47, v252, 7
	v_readlane_b32 s48, v252, 8
	v_readlane_b32 s49, v252, 9
	v_readlane_b32 s50, v252, 10
	v_readlane_b32 s51, v252, 11
	v_readlane_b32 s52, v252, 12
	v_readlane_b32 s53, v252, 13
	v_readlane_b32 s54, v252, 14
	v_readlane_b32 s55, v252, 15
	v_readlane_b32 s56, v252, 16
	v_readlane_b32 s57, v252, 17
	v_readlane_b32 s58, v252, 18
	v_readlane_b32 s59, v252, 19
	s_cbranch_scc1 .LBB0_224
	s_and_b64 s[4:5], s[12:13], exec
	s_mov_b32 s4, 0x4c25000
	s_cselect_b32 s4, s4, 0x9c25000
	s_add_u32 s4, s58, s4
	s_addc_u32 s5, s59, 0
	s_and_b64 s[20:21], s[12:13], exec
	s_mov_b32 s20, 0xfd25000
	s_cselect_b32 s20, s20, 0x6425000
	s_add_u32 s22, s58, s20
	v_readlane_b32 s14, v255, 2
	s_addc_u32 s23, s59, 0
	s_lshl_b32 s20, s14, 7
	s_mov_b64 s[36:37], s[44:45]
	s_ashr_i32 s21, s20, 31
	s_mov_b64 s[38:39], s[46:47]
	s_mov_b64 s[40:41], s[48:49]
	s_mov_b64 s[42:43], s[50:51]
	s_mov_b64 s[44:45], s[52:53]
	s_mov_b64 s[46:47], s[54:55]
	s_mov_b64 s[48:49], s[56:57]
	s_mov_b64 s[50:51], s[58:59]
	v_readlane_b32 s52, v253, 8
	s_lshl_b64 s[20:21], s[20:21], 2
	v_readlane_b32 s66, v253, 22
	v_readlane_b32 s53, v253, 9
	v_readlane_b32 s54, v253, 10
	v_readlane_b32 s55, v253, 11
	v_readlane_b32 s56, v253, 12
	v_readlane_b32 s57, v253, 13
	v_readlane_b32 s58, v253, 14
	v_readlane_b32 s59, v253, 15
	v_readlane_b32 s67, v253, 23
	s_add_u32 s26, s66, s20
	s_mov_b64 s[58:59], s[50:51]
	s_mov_b32 s75, 0x60000
	s_mov_b32 s76, 0x8000
	s_addc_u32 s27, s67, s21
	s_nop 0
	v_readlane_b32 s15, v255, 3
	v_readlane_b32 s60, v253, 16
	v_readlane_b32 s61, v253, 17
	v_readlane_b32 s62, v253, 18
	v_readlane_b32 s63, v253, 19
	v_readlane_b32 s64, v253, 20
	v_readlane_b32 s65, v253, 21
	s_mov_b64 s[56:57], s[48:49]
	s_mov_b64 s[54:55], s[46:47]
	s_mov_b64 s[52:53], s[44:45]
	s_mov_b64 s[50:51], s[42:43]
	s_mov_b64 s[48:49], s[40:41]
	s_mov_b64 s[46:47], s[38:39]
	s_mov_b64 s[44:45], s[36:37]
	s_cmp_eq_u32 s6, 35
	s_cbranch_scc0 .Lfin_go2
	v_readlane_b32 s98, v255, 13
	v_readlane_b32 s99, v255, 14
	s_mov_b32 vcc_lo, 0
	s_nop 4

.Lfin_go2:
	s_cmp_eq_u32 s6, 35
	s_cselect_b32 s98, 0x100, 0
	s_sub_i32 s99, 0x200, s98
	s_sub_i32 s21, s71, s98
	s_lshl_b32 s20, s21, 5
	s_lshl_b32 s30, s99, 5
.LBB0_223:
	v_mov_b32_e32 v0, v1
	s_add_i32 s21, s21, s99
	v_mbcnt_lo_u32_b32 v0, -1, v0
	v_mbcnt_hi_u32_b32 v0, -1, v0
	v_add_u32_e32 v0, s80, v0
	s_nop 0
	v_ashrrev_i32_e32 v6, 3, v0
	s_waitcnt lgkmcnt(0)
	v_add_u32_e32 v2, s20, v6
	v_ashrrev_i32_e32 v2, 2, v2
	v_ashrrev_i32_e32 v3, 31, v2
	v_lshlrev_b64 v[4:5], 9, v[2:3]
	v_lshlrev_b32_e32 v3, 7, v6
	v_and_b32_e32 v8, 0x180, v3
	v_lshlrev_b32_e32 v0, 4, v0
	v_mov_b64_e32 v[6:7], s[58:59]
	v_and_b32_e32 v22, 0x70, v0
	v_mad_i64_i32 v[2:3], s[24:25], v2, s31, v[6:7]
	v_lshlrev_b32_e32 v0, 1, v8
	v_lshl_add_u64 v[2:3], v[2:3], 0, v[0:1]
	v_lshlrev_b32_e32 v0, 1, v22
	v_or3_b32 v4, v4, v8, v22
	v_lshl_add_u64 v[2:3], v[2:3], 0, v[0:1]
	v_lshlrev_b64 v[6:7], 1, v[4:5]
	v_lshl_add_u64 v[20:21], v[2:3], 0, s[34:35]
	v_add_co_u32_e32 v2, vcc, s2, v2
	v_lshl_add_u64 v[32:33], v[4:5], 2, s[4:5]
	v_lshl_add_u64 v[4:5], s[22:23], 0, v[6:7]
	v_addc_co_u32_e32 v3, vcc, 0, v3, vcc
	global_load_dwordx4 v[8:11], v[4:5], off
	global_load_dwordx4 v[12:15], v[4:5], off offset:16
	v_cmp_lt_i32_e32 vcc, v227, v221
	global_load_dwordx4 v[16:19], v[2:3], off
	s_nop 0
	global_load_dwordx4 v[2:5], v[20:21], off offset:16
	v_cndmask_b32_e32 v20, v220, v227, vcc
	v_cmp_lt_i32_e32 vcc, v226, v221
	v_lshlrev_b32_e32 v70, 2, v20
	v_lshlrev_b32_e32 v0, 2, v22
	v_cndmask_b32_e32 v20, v220, v226, vcc
	v_cmp_lt_i32_e32 vcc, v235, v221
	v_lshlrev_b32_e32 v71, 2, v20
	v_lshl_add_u64 v[6:7], s[28:29], 0, v[6:7]
	v_cndmask_b32_e32 v20, v220, v235, vcc
	v_lshlrev_b32_e32 v72, 2, v20
	global_load_dwordx4 v[20:23], v[32:33], off offset:48
	global_load_dwordx4 v[24:27], v[32:33], off offset:32
	global_load_dwordx4 v[28:31], v[32:33], off offset:16
	s_nop 0
	global_load_dwordx4 v[32:35], v[32:33], off
	s_add_i32 s20, s20, s30
	s_cmpk_gt_i32 s21, 0x3ff
	s_waitcnt vmcnt(0)
	v_lshlrev_b32_e32 v36, 16, v15
	v_and_b32_e32 v37, 0xffff0000, v15
	s_waitcnt vmcnt(4)
	v_and_b32_e32 v55, 0xffff0000, v4
	v_lshlrev_b32_e32 v58, 16, v3
	v_and_b32_e32 v59, 0xffff0000, v3
	v_lshlrev_b32_e32 v54, 16, v4
	v_mul_f32_e32 v4, 0xbfb8aa3b, v54
	v_exp_f32_e32 v4, v4
	v_lshlrev_b32_e32 v62, 16, v19
	v_and_b32_e32 v63, 0xffff0000, v19
	s_waitcnt vmcnt(3)
	v_pk_add_f32 v[48:49], v[22:23], v[36:37]
	v_lshlrev_b32_e32 v22, 16, v14
	v_and_b32_e32 v23, 0xffff0000, v14
	v_pk_add_f32 v[14:15], v[20:21], v[22:23]
	global_load_dwordx4 v[20:23], v0, s[26:27] offset:48
	global_load_dwordx4 v[36:39], v0, s[26:27] offset:32
	global_load_dwordx4 v[40:43], v0, s[26:27] offset:16
	global_load_dwordx4 v[44:47], v0, s[26:27]
	v_mul_f32_e32 v0, 0xbfb8aa3b, v55
	v_exp_f32_e32 v0, v0
	v_add_f32_e32 v4, 1.0, v4
	v_rcp_f32_e32 v56, v4
	v_lshlrev_b32_e32 v66, 16, v17
	v_add_f32_e32 v0, 1.0, v0
	v_rcp_f32_e32 v57, v0
	v_mul_f32_e32 v0, 0xbfb8aa3b, v58
	v_exp_f32_e32 v0, v0
	v_and_b32_e32 v67, 0xffff0000, v17
	v_pk_mul_f32 v[54:55], v[56:57], v[54:55]
	v_lshlrev_b32_e32 v56, 16, v13
	v_add_f32_e32 v0, 1.0, v0
	v_rcp_f32_e32 v60, v0
	v_mul_f32_e32 v0, 0xbfb8aa3b, v59
	v_exp_f32_e32 v0, v0
	v_and_b32_e32 v57, 0xffff0000, v13
	s_waitcnt vmcnt(6)
	v_pk_add_f32 v[26:27], v[26:27], v[56:57]
	v_pk_mul_f32 v[52:53], v[14:15], v[14:15]
	v_add_f32_e32 v0, 1.0, v0
	v_rcp_f32_e32 v61, v0
	v_pk_mul_f32 v[56:57], v[26:27], v[26:27]
	v_pk_mul_f32 v[50:51], v[48:49], v[48:49]
	v_pk_mul_f32 v[58:59], v[60:61], v[58:59]
	v_lshlrev_b32_e32 v60, 16, v12
	v_and_b32_e32 v61, 0xffff0000, v12
	v_pk_add_f32 v[12:13], v[24:25], v[60:61]
	v_lshlrev_b32_e32 v60, 16, v2
	v_mul_f32_e32 v0, 0xbfb8aa3b, v60
	v_exp_f32_e32 v0, v0
	v_and_b32_e32 v61, 0xffff0000, v2
	v_pk_mul_f32 v[24:25], v[12:13], v[12:13]
	v_add_f32_e32 v0, 1.0, v0
	v_rcp_f32_e32 v2, v0
	v_mul_f32_e32 v0, 0xbfb8aa3b, v61
	v_exp_f32_e32 v0, v0
	s_nop 0
	v_add_f32_e32 v0, 1.0, v0
	v_rcp_f32_e32 v3, v0
	v_mul_f32_e32 v0, 0xbfb8aa3b, v62
	v_exp_f32_e32 v0, v0
	v_pk_mul_f32 v[2:3], v[2:3], v[60:61]
	v_lshlrev_b32_e32 v60, 16, v11
	v_add_f32_e32 v0, 1.0, v0
	v_rcp_f32_e32 v64, v0
	v_mul_f32_e32 v0, 0xbfb8aa3b, v63
	v_exp_f32_e32 v0, v0
	v_and_b32_e32 v61, 0xffff0000, v11
	s_waitcnt vmcnt(5)
	v_pk_add_f32 v[30:31], v[30:31], v[60:61]
	v_add_f32_e32 v0, 1.0, v0
	v_rcp_f32_e32 v65, v0
	v_pk_mul_f32 v[60:61], v[30:31], v[30:31]
	v_pk_mul_f32 v[62:63], v[64:65], v[62:63]
	v_lshlrev_b32_e32 v64, 16, v10
	v_and_b32_e32 v65, 0xffff0000, v10
	v_pk_add_f32 v[10:11], v[28:29], v[64:65]
	v_lshlrev_b32_e32 v64, 16, v18
	v_mul_f32_e32 v0, 0xbfb8aa3b, v64
	v_exp_f32_e32 v0, v0
	v_and_b32_e32 v65, 0xffff0000, v18
	v_pk_mul_f32 v[28:29], v[10:11], v[10:11]
	v_add_f32_e32 v0, 1.0, v0
	v_rcp_f32_e32 v18, v0
	v_mul_f32_e32 v0, 0xbfb8aa3b, v65
	v_exp_f32_e32 v0, v0
	s_nop 0
	v_add_f32_e32 v0, 1.0, v0
	v_rcp_f32_e32 v19, v0
	v_mul_f32_e32 v0, 0xbfb8aa3b, v66
	v_exp_f32_e32 v0, v0
	v_pk_mul_f32 v[18:19], v[18:19], v[64:65]
	v_lshlrev_b32_e32 v64, 16, v9
	v_add_f32_e32 v0, 1.0, v0
	v_rcp_f32_e32 v68, v0
	v_mul_f32_e32 v0, 0xbfb8aa3b, v67
	v_exp_f32_e32 v0, v0
	v_and_b32_e32 v65, 0xffff0000, v9
	s_waitcnt vmcnt(4)
	v_pk_add_f32 v[34:35], v[34:35], v[64:65]
	v_add_f32_e32 v0, 1.0, v0
	v_rcp_f32_e32 v69, v0
	v_pk_mul_f32 v[64:65], v[34:35], v[34:35]
	v_pk_mul_f32 v[66:67], v[68:69], v[66:67]
	v_lshlrev_b32_e32 v68, 16, v8
	v_and_b32_e32 v69, 0xffff0000, v8
	v_pk_add_f32 v[8:9], v[32:33], v[68:69]
	v_lshlrev_b32_e32 v68, 16, v16
	v_mul_f32_e32 v0, 0xbfb8aa3b, v68
	v_exp_f32_e32 v0, v0
	v_and_b32_e32 v69, 0xffff0000, v16
	v_pk_mul_f32 v[32:33], v[8:9], v[8:9]
	v_add_f32_e32 v0, 1.0, v0
	v_rcp_f32_e32 v16, v0
	v_mul_f32_e32 v0, 0xbfb8aa3b, v69
	v_exp_f32_e32 v0, v0
	s_nop 0
	v_add_f32_e32 v0, 1.0, v0
	v_rcp_f32_e32 v17, v0
	v_add_f32_e32 v0, v32, v33
	v_add_f32_e32 v0, v64, v0
	v_add_f32_e32 v0, v65, v0
	v_add_f32_e32 v0, v28, v0
	v_add_f32_e32 v0, v29, v0
	v_add_f32_e32 v0, v60, v0
	v_add_f32_e32 v0, v61, v0
	v_add_f32_e32 v0, v24, v0
	v_add_f32_e32 v0, v25, v0
	v_add_f32_e32 v0, v56, v0
	v_add_f32_e32 v0, v57, v0
	v_add_f32_e32 v0, v52, v0
	v_add_f32_e32 v0, v53, v0
	v_add_f32_e32 v0, v50, v0
	v_add_f32_e32 v0, v51, v0
	ds_bpermute_b32 v4, v70, v0
	v_pk_mul_f32 v[16:17], v[16:17], v[68:69]
	s_waitcnt lgkmcnt(0)
	v_add_f32_e32 v0, v0, v4
	ds_bpermute_b32 v4, v71, v0
	s_waitcnt lgkmcnt(0)
	v_add_f32_e32 v0, v0, v4
	ds_bpermute_b32 v4, v72, v0
	s_waitcnt lgkmcnt(0)
	v_add_f32_e32 v0, v0, v4
	v_fmamk_f32 v0, v0, 0x3c000000, v187
	v_cmp_gt_f32_e32 vcc, s82, v0
	v_mul_f32_e32 v4, 0x4b800000, v0
	s_nop 0
	v_cndmask_b32_e32 v0, v0, v4, vcc
	v_rsq_f32_e32 v0, v0
	s_nop 0
	v_mul_f32_e32 v4, 0x45800000, v0
	v_cndmask_b32_e32 v0, v0, v4, vcc
	v_pk_mul_f32 v[12:13], v[12:13], v[0:1] op_sel_hi:[1,0]
	v_pk_mul_f32 v[8:9], v[8:9], v[0:1] op_sel_hi:[1,0]
	s_waitcnt vmcnt(2)
	v_pk_mul_f32 v[12:13], v[36:37], v[12:13]
	s_waitcnt vmcnt(0)
	v_pk_mul_f32 v[8:9], v[44:45], v[8:9]
	v_pk_mul_f32 v[12:13], v[2:3], v[12:13]
	v_pk_mul_f32 v[2:3], v[34:35], v[0:1] op_sel_hi:[1,0]
	v_pk_mul_f32 v[8:9], v[16:17], v[8:9]
	v_pk_mul_f32 v[2:3], v[46:47], v[2:3]
	s_nop 0
	v_pk_mul_f32 v[16:17], v[66:67], v[2:3]
	v_pk_mul_f32 v[2:3], v[26:27], v[0:1] op_sel_hi:[1,0]
	s_nop 0
	v_pk_mul_f32 v[2:3], v[38:39], v[2:3]
	s_nop 0
	v_pk_mul_f32 v[24:25], v[58:59], v[2:3]
	v_pk_mul_f32 v[2:3], v[10:11], v[0:1] op_sel_hi:[1,0]
	s_nop 0
	v_pk_mul_f32 v[2:3], v[40:41], v[2:3]
	s_nop 0
	v_pk_mul_f32 v[10:11], v[18:19], v[2:3]
	v_pk_mul_f32 v[2:3], v[14:15], v[0:1] op_sel_hi:[1,0]
	s_nop 0
	v_pk_mul_f32 v[2:3], v[20:21], v[2:3]
	v_pk_mul_f32 v[20:21], v[48:49], v[0:1] op_sel_hi:[1,0]
	v_pk_mul_f32 v[14:15], v[54:55], v[2:3]
	v_pk_mul_f32 v[2:3], v[30:31], v[0:1] op_sel_hi:[1,0]
	v_pk_mul_f32 v[20:21], v[22:23], v[20:21]
	v_pk_mul_f32 v[2:3], v[42:43], v[2:3]
	s_nop 0
	v_pk_mul_f32 v[18:19], v[62:63], v[2:3]
	v_lshlrev_b32_e32 v2, 16, v5
	v_and_b32_e32 v3, 0xffff0000, v5
	v_mul_f32_e32 v4, 0xbfb8aa3b, v2
	v_mul_f32_e32 v0, 0xbfb8aa3b, v3
	v_exp_f32_e32 v4, v4
	v_exp_f32_e32 v0, v0
	v_add_f32_e32 v4, 1.0, v4
	v_add_f32_e32 v0, 1.0, v0
	v_rcp_f32_e32 v4, v4
	v_rcp_f32_e32 v5, v0
	s_nop 0
	v_pk_mul_f32 v[2:3], v[4:5], v[2:3]
	s_nop 0
	v_pk_mul_f32 v[20:21], v[2:3], v[20:21]
	v_cvt_pk_bf16_f32 v2, v8, v9
	v_cvt_pk_bf16_f32 v3, v16, v17
	v_cvt_pk_bf16_f32 v4, v10, v11
	v_cvt_pk_bf16_f32 v5, v18, v19
	global_store_dwordx4 v[6:7], v[2:5], off
	s_nop 1
	v_cvt_pk_bf16_f32 v2, v12, v13
	v_cvt_pk_bf16_f32 v3, v24, v25
	v_cvt_pk_bf16_f32 v4, v14, v15
	v_cvt_pk_bf16_f32 v5, v20, v21
	global_store_dwordx4 v[6:7], v[2:5], off offset:16
	s_cbranch_scc0 .LBB0_223

.Lp2done:
	s_cmp_lg_u32 s6, 34
	s_cbranch_scc1 .Lp2done_x
	s_waitcnt vmcnt(0) lgkmcnt(0)
	s_barrier
	s_cmp_lg_u32 s80, 0
	s_cbranch_scc1 .Lp2done_x
	buffer_wbl2 sc1
	s_waitcnt vmcnt(0)
	v_readlane_b32 s98, v255, 13
	v_readlane_b32 s99, v255, 14
	s_mov_b64 s[4:5], exec
	s_mov_b64 exec, 1
	v_mov_b32_e32 v2, 1
	s_nop 4
	global_atomic_add v1, v2, s[98:99]
	s_mov_b64 exec, s[4:5]
